# row-statistics loads of first epilogue batched (16 loads in flight instead of 8 serial round trips), 3 sites
# baseline (speedup 1.0000x reference)
; __device__ __forceinline__ float rowsum32(const float* ssp, int row, int nsl4, int fq) {
;     f32x4 v = {0.f, 0.f, 0.f, 0.f};
;     if (fq < nsl4) v = *(const f32x4*)(ssp + (size_t)row * 32 + 4 * fq);
;     if (fq + 4 < nsl4) v = v + *(const f32x4*)(ssp + (size_t)row * 32 + 4 * (fq + 4));
;     float s = (v[0] + v[1]) + (v[2] + v[3]);
;     s += __shfl_xor(s, 16); s += __shfl_xor(s, 32);
;     return s;
;     __device__ __forceinline__ void operator()(const f32x4 (&acc)[2][2][4][2], const Unit& u, int wr, int wc, int fr, int fq) const {
;         const int row0 = u.pm * BM + wr * 64 + fr;
;         float rsa[2][4];
;         if (u.pm != last_pm) {
; #pragma unroll
;             for (int ai = 0; ai < 2; ++ai)
; #pragma unroll
;                 for (int m = 0; m < 4; ++m) { rsa[ai][m] = __builtin_amdgcn_rsqf(rowsum32(ss, row0 + ai * HALF + m * 16, 8, fq) * inv_w + RMS_EPS); tab[ai * HALF + wr * 64 + m * 16 + fr] = rsa[ai][m]; }
;             last_pm = u.pm;
.LBB0_313:
	v_lshl_add_u32 v184, s23, 8, v1
	v_or_b32_e32 v172, 16, v184
	v_or_b32_e32 v168, 32, v184
	v_or_b32_e32 v162, 48, v184
	v_add_u32_e32 v158, 0x80, v184
	v_add_u32_e32 v156, 0x90, v184
	v_add_u32_e32 v154, 0xa0, v184
	v_add_u32_e32 v152, 0xb0, v184
	s_mov_b64 s[52:53], -1
	s_cmp_eq_u32 s23, s79
	v_ashrrev_i32_e32 v185, 31, v184
	v_ashrrev_i32_e32 v173, 31, v172
	v_ashrrev_i32_e32 v169, 31, v168
	v_ashrrev_i32_e32 v163, 31, v162
	v_ashrrev_i32_e32 v159, 31, v158
	v_ashrrev_i32_e32 v157, 31, v156
	v_ashrrev_i32_e32 v155, 31, v154
	v_ashrrev_i32_e32 v153, 31, v152
	s_cbranch_scc1 .LBB0_315
	s_mov_b64 s[52:53], 0
	v_lshlrev_b32_e32 v136, 7, v184
	v_mov_b32_e32 v137, 0
	v_add_u32_e32 v136, 0x1000, v136
	v_mov_b32_e32 v197, 0
	v_add_u32_e32 v196, 0x4000, v136
	v_lshl_add_u64 v[136:137], v[146:147], 0, v[136:137]
	v_lshl_add_u64 v[196:197], v[146:147], 0, v[196:197]
	global_load_dwordx4 v[204:207], v[136:137], off offset:-4096
	global_load_dwordx4 v[208:211], v[136:137], off offset:-4032
	global_load_dwordx4 v[212:215], v[136:137], off offset:-2048
	global_load_dwordx4 v[216:219], v[136:137], off offset:-1984
	global_load_dwordx4 v[220:223], v[136:137], off
	global_load_dwordx4 v[224:227], v[136:137], off offset:64
	global_load_dwordx4 v[228:231], v[136:137], off offset:2048
	global_load_dwordx4 v[232:235], v[136:137], off offset:2112
	global_load_dwordx4 v[236:239], v[196:197], off offset:-4096
	global_load_dwordx4 v[188:191], v[196:197], off offset:-4032
	global_load_dwordx4 v[192:195], v[196:197], off offset:-2048
	global_load_dwordx4 v[132:135], v[196:197], off offset:-1984
	v_and_b32_e32 v160, 64, v200
	v_xor_b32_e32 v131, 16, v200
	v_add_u32_e32 v160, 64, v160
	v_xor_b32_e32 v187, 32, v200
	v_cmp_lt_i32_e32 vcc, v131, v160
	s_nop 1
	v_cndmask_b32_e32 v131, v200, v131, vcc
	v_cmp_lt_i32_e32 vcc, v187, v160
	v_lshlrev_b32_e32 v167, 2, v131
	s_nop 1
	v_cndmask_b32_e32 v187, v200, v187, vcc
	v_lshlrev_b32_e32 v161, 2, v187
	s_waitcnt vmcnt(10)
	v_add_f32_e32 v204, v204, v208
	v_add_f32_e32 v205, v205, v209
	v_add_f32_e32 v206, v206, v210
	v_add_f32_e32 v207, v207, v211
	v_add_f32_e32 v204, v204, v205
	v_add_f32_e32 v206, v206, v207
	v_add_f32_e32 v186, v204, v206
	global_load_dwordx4 v[204:207], v[196:197], off
	global_load_dwordx4 v[208:211], v[196:197], off offset:64
	s_waitcnt vmcnt(10)
	v_add_f32_e32 v212, v212, v216
	v_add_f32_e32 v213, v213, v217
	v_add_f32_e32 v214, v214, v218
	v_add_f32_e32 v215, v215, v219
	v_add_f32_e32 v212, v212, v213
	v_add_f32_e32 v214, v214, v215
	v_add_f32_e32 v182, v212, v214
	global_load_dwordx4 v[212:215], v[196:197], off offset:2048
	global_load_dwordx4 v[216:219], v[196:197], off offset:2112
	s_waitcnt vmcnt(10)
	v_add_f32_e32 v220, v220, v224
	v_add_f32_e32 v221, v221, v225
	v_add_f32_e32 v222, v222, v226
	v_add_f32_e32 v223, v223, v227
	v_add_f32_e32 v220, v220, v221
	v_add_f32_e32 v222, v222, v223
	v_add_f32_e32 v176, v220, v222
	s_waitcnt vmcnt(8)
	v_add_f32_e32 v228, v228, v232
	v_add_f32_e32 v229, v229, v233
	v_add_f32_e32 v230, v230, v234
	v_add_f32_e32 v231, v231, v235
	v_add_f32_e32 v228, v228, v229
	v_add_f32_e32 v230, v230, v231
	v_add_f32_e32 v170, v228, v230
	s_waitcnt vmcnt(6)
	v_add_f32_e32 v236, v236, v188
	v_add_f32_e32 v237, v237, v189
	v_add_f32_e32 v238, v238, v190
	v_add_f32_e32 v239, v239, v191
	v_add_f32_e32 v236, v236, v237
	v_add_f32_e32 v238, v238, v239
	v_add_f32_e32 v166, v236, v238
	s_waitcnt vmcnt(4)
	v_add_f32_e32 v192, v192, v132
	v_add_f32_e32 v193, v193, v133
	v_add_f32_e32 v194, v194, v134
	v_add_f32_e32 v195, v195, v135
	v_add_f32_e32 v192, v192, v193
	v_add_f32_e32 v194, v194, v195
	v_add_f32_e32 v164, v192, v194
	s_waitcnt vmcnt(2)
	v_add_f32_e32 v204, v204, v208
	v_add_f32_e32 v205, v205, v209
	v_add_f32_e32 v206, v206, v210
	v_add_f32_e32 v207, v207, v211
	v_add_f32_e32 v204, v204, v205
	v_add_f32_e32 v206, v206, v207
	v_add_f32_e32 v160, v204, v206
	s_waitcnt vmcnt(0)
	v_add_f32_e32 v212, v212, v216
	v_add_f32_e32 v213, v213, v217
	v_add_f32_e32 v214, v214, v218
	v_add_f32_e32 v215, v215, v219
	v_add_f32_e32 v212, v212, v213
	v_add_f32_e32 v214, v214, v215
	v_add_f32_e32 v130, v212, v214
	ds_bpermute_b32 v204, v167, v186
	ds_bpermute_b32 v205, v167, v182
	ds_bpermute_b32 v206, v167, v176
	ds_bpermute_b32 v207, v167, v170
	ds_bpermute_b32 v208, v167, v166
	ds_bpermute_b32 v209, v167, v164
	ds_bpermute_b32 v210, v167, v160
	ds_bpermute_b32 v211, v167, v130
	s_waitcnt lgkmcnt(0)
	v_add_f32_e32 v186, v186, v204
	v_add_f32_e32 v182, v182, v205
	v_add_f32_e32 v176, v176, v206
	v_add_f32_e32 v170, v170, v207
	v_add_f32_e32 v166, v166, v208
	v_add_f32_e32 v164, v164, v209
	v_add_f32_e32 v160, v160, v210
	v_add_f32_e32 v130, v130, v211
	ds_bpermute_b32 v204, v161, v186
	ds_bpermute_b32 v205, v161, v182
	ds_bpermute_b32 v206, v161, v176
	ds_bpermute_b32 v207, v161, v170
	ds_bpermute_b32 v208, v161, v166
	ds_bpermute_b32 v209, v161, v164
	ds_bpermute_b32 v210, v161, v160
	ds_bpermute_b32 v211, v161, v130
	s_waitcnt lgkmcnt(0)
	v_add_f32_e32 v186, v186, v204
	v_add_f32_e32 v182, v182, v205
	v_add_f32_e32 v176, v176, v206
	v_add_f32_e32 v170, v170, v207
	v_add_f32_e32 v166, v166, v208
	v_add_f32_e32 v164, v164, v209
	v_add_f32_e32 v160, v160, v210
	v_add_f32_e32 v130, v130, v211
	v_fmamk_f32 v186, v186, 0x3a000000, v199
	v_fmamk_f32 v182, v182, 0x3a000000, v199
	v_fmamk_f32 v176, v176, 0x3a000000, v199
	v_fmamk_f32 v170, v170, 0x3a000000, v199
	v_fmamk_f32 v166, v166, 0x3a000000, v199
	v_fmamk_f32 v164, v164, 0x3a000000, v199
	v_fmamk_f32 v160, v160, 0x3a000000, v199
	v_fmamk_f32 v130, v130, 0x3a000000, v199
	v_rsq_f32_e32 v186, v186
	v_rsq_f32_e32 v182, v182
	v_rsq_f32_e32 v176, v176
	v_rsq_f32_e32 v170, v170
	v_rsq_f32_e32 v166, v166
	v_rsq_f32_e32 v164, v164
	v_rsq_f32_e32 v160, v160
	v_rsq_f32_e32 v130, v130
	ds_write2_b32 v171, v186, v182 offset1:16
	ds_write2_b32 v171, v176, v170 offset0:32 offset1:48
	ds_write2_b32 v171, v166, v164 offset0:128 offset1:144
	ds_write2_b32 v171, v160, v130 offset0:160 offset1:176

; __device__ __forceinline__ float rowsum32(const float* ssp, int row, int nsl4, int fq) {
;     f32x4 v = {0.f, 0.f, 0.f, 0.f};
;     if (fq < nsl4) v = *(const f32x4*)(ssp + (size_t)row * 32 + 4 * fq);
;     if (fq + 4 < nsl4) v = v + *(const f32x4*)(ssp + (size_t)row * 32 + 4 * (fq + 4));
;     __device__ __forceinline__ void operator()(const f32x4 (&acc)[2][2][4][2], const Unit& u, int wr, int wc, int fr, int fq) const {
;         const int row0 = u.pm * BM + wr * 64 + fr;
;         const float sc = (u.pn < nscale) ? scale : 1.f;
;         float* sacc = nullptr; int slot0 = 0;
;         if (u.pn >= a_lo && u.pn < a_hi) { sacc = ssA; slot0 = (u.pn - a_lo) * 4 + wc; } else if (u.pn >= b_lo && u.pn < b_hi) { sacc = ssB; slot0 = (u.pn - b_lo) * 4 + wc; }
;         float rs[2][4];
;         if (!ss) {
; #pragma unroll
;             for (int ai = 0; ai < 2; ++ai)
; #pragma unroll
;                 for (int m = 0; m < 4; ++m) rs[ai][m] = sc;
;         } else if (u.pm != last_pm) {
; #pragma unroll
;             for (int ai = 0; ai < 2; ++ai)
; #pragma unroll
;                 for (int m = 0; m < 4; ++m) { const int row = row0 + ai * HALF + m * 16; const float r_ = __builtin_amdgcn_rsqf(rowsum32(ss, row, nsl4, fq) * inv_w + RMS_EPS);
;                     tab[ai * HALF + wr * 64 + m * 16 + fr] = r_; rs[ai][m] = r_ * sc; }
.LBB0_405:
	v_readlane_b32 s13, v248, 4
	s_cmp_lt_i32 s33, s13
	v_readlane_b32 s13, v248, 5
	s_cselect_b64 vcc, -1, 0
	v_lshl_add_u32 v172, s12, 8, v1
	v_mov_b32_e32 v130, s13
	v_cndmask_b32_e32 v182, 1.0, v130, vcc
	s_andn2_b64 vcc, exec, s[14:15]
	s_cbranch_vccnz .LBB0_443
	s_cmp_eq_u32 s12, s19
	s_mov_b64 s[46:47], -1
	s_cbranch_scc1 .LBB0_440
	v_mov_b32_e32 v174, v175
	v_mov_b64_e32 v[132:133], 0
	v_mov_b64_e32 v[134:135], 0
	v_mov_b64_e32 v[136:137], 0
	v_mov_b64_e32 v[138:139], 0
	v_mov_b64_e32 v[140:141], 0
	v_mov_b64_e32 v[142:143], 0
	v_mov_b64_e32 v[144:145], 0
	v_mov_b64_e32 v[146:147], 0
	v_mov_b64_e32 v[148:149], 0
	v_mov_b64_e32 v[150:151], 0
	v_mov_b64_e32 v[188:189], 0
	v_mov_b64_e32 v[190:191], 0
	v_mov_b64_e32 v[192:193], 0
	v_mov_b64_e32 v[194:195], 0
	v_mov_b64_e32 v[206:207], 0
	v_mov_b64_e32 v[208:209], 0
	v_mov_b64_e32 v[210:211], 0
	v_mov_b64_e32 v[212:213], 0
	v_mov_b64_e32 v[214:215], 0
	v_mov_b64_e32 v[216:217], 0
	v_mov_b64_e32 v[218:219], 0
	v_mov_b64_e32 v[220:221], 0
	v_mov_b64_e32 v[222:223], 0
	v_mov_b64_e32 v[224:225], 0
	v_mov_b64_e32 v[226:227], 0
	v_mov_b64_e32 v[228:229], 0
	v_mov_b64_e32 v[230:231], 0
	v_mov_b64_e32 v[232:233], 0
	v_mov_b64_e32 v[234:235], 0
	v_mov_b64_e32 v[236:237], 0
	v_mov_b64_e32 v[184:185], 0
	v_mov_b64_e32 v[186:187], 0
	v_lshlrev_b32_e32 v130, 7, v172
	v_mov_b32_e32 v131, 0
	v_add_u32_e32 v130, 0x1000, v130
	v_lshl_add_u64 v[152:153], v[164:165], 0, v[130:131]
	v_lshl_add_u64 v[196:197], v[166:167], 0, v[130:131]
	v_mov_b32_e32 v130, 0x4000
	v_lshl_add_u64 v[238:239], v[152:153], 0, v[130:131]
	v_lshl_add_u64 v[176:177], v[196:197], 0, v[130:131]
	s_and_saveexec_b64 s[46:47], s[40:41]
	s_cbranch_execz .Lrs_bfa_lo_done
	global_load_dwordx4 v[132:135], v[152:153], off offset:-4096
	global_load_dwordx4 v[140:143], v[152:153], off offset:-2048
	global_load_dwordx4 v[148:151], v[152:153], off
	global_load_dwordx4 v[192:195], v[152:153], off offset:2048
	global_load_dwordx4 v[210:213], v[238:239], off offset:-4096
	global_load_dwordx4 v[218:221], v[238:239], off offset:-2048
	global_load_dwordx4 v[226:229], v[238:239], off
	global_load_dwordx4 v[234:237], v[238:239], off offset:2048
.Lrs_bfa_lo_done:
	s_or_b64 exec, exec, s[46:47]
	s_and_saveexec_b64 s[46:47], s[42:43]
	s_cbranch_execz .Lrs_bfa_hi_done
	global_load_dwordx4 v[136:139], v[196:197], off offset:-4096
	global_load_dwordx4 v[144:147], v[196:197], off offset:-2048
	global_load_dwordx4 v[188:191], v[196:197], off
	global_load_dwordx4 v[206:209], v[196:197], off offset:2048
	global_load_dwordx4 v[214:217], v[176:177], off offset:-4096
	global_load_dwordx4 v[222:225], v[176:177], off offset:-2048
	global_load_dwordx4 v[230:233], v[176:177], off
	global_load_dwordx4 v[184:187], v[176:177], off offset:2048
; __device__ __forceinline__ float rowsum32(const float* ssp, int row, int nsl4, int fq) {
;     f32x4 v = {0.f, 0.f, 0.f, 0.f};
;     if (fq < nsl4) v = *(const f32x4*)(ssp + (size_t)row * 32 + 4 * fq);
;     if (fq + 4 < nsl4) v = v + *(const f32x4*)(ssp + (size_t)row * 32 + 4 * (fq + 4));
;     float s = (v[0] + v[1]) + (v[2] + v[3]);
;     s += __shfl_xor(s, 16); s += __shfl_xor(s, 32);
;     return s;
;     __device__ __forceinline__ void operator()(const f32x4 (&acc)[2][2][4][2], const Unit& u, int wr, int wc, int fr, int fq) const {
;     ...
;         } else if (u.pm != last_pm) {
; #pragma unroll
;             for (int ai = 0; ai < 2; ++ai)
; #pragma unroll
;                 for (int m = 0; m < 4; ++m) { const int row = row0 + ai * HALF + m * 16; const float r_ = __builtin_amdgcn_rsqf(rowsum32(ss, row, nsl4, fq) * inv_w + RMS_EPS);
;                     tab[ai * HALF + wr * 64 + m * 16 + fr] = r_; rs[ai][m] = r_ * sc; }
;             last_pm = u.pm;
.Lrs_bfa_hi_done:
	s_or_b64 exec, exec, s[46:47]
	v_and_b32_e32 v153, 64, v200
	v_xor_b32_e32 v130, 16, v200
	v_add_u32_e32 v153, 64, v153
	v_xor_b32_e32 v131, 32, v200
	v_cmp_lt_i32_e32 vcc, v130, v153
	s_nop 1
	v_cndmask_b32_e32 v130, v200, v130, vcc
	v_cmp_lt_i32_e32 vcc, v131, v153
	v_lshlrev_b32_e32 v197, 2, v130
	s_nop 1
	v_cndmask_b32_e32 v131, v200, v131, vcc
	v_lshlrev_b32_e32 v239, 2, v131
	s_waitcnt vmcnt(0)
	v_add_f32_e32 v132, v132, v136
	v_add_f32_e32 v133, v133, v137
	v_add_f32_e32 v134, v134, v138
	v_add_f32_e32 v135, v135, v139
	v_add_f32_e32 v132, v132, v133
	v_add_f32_e32 v134, v134, v135
	v_add_f32_e32 v132, v132, v134
	v_add_f32_e32 v140, v140, v144
	v_add_f32_e32 v141, v141, v145
	v_add_f32_e32 v142, v142, v146
	v_add_f32_e32 v143, v143, v147
	v_add_f32_e32 v140, v140, v141
	v_add_f32_e32 v142, v142, v143
	v_add_f32_e32 v140, v140, v142
	v_add_f32_e32 v148, v148, v188
	v_add_f32_e32 v149, v149, v189
	v_add_f32_e32 v150, v150, v190
	v_add_f32_e32 v151, v151, v191
	v_add_f32_e32 v148, v148, v149
	v_add_f32_e32 v150, v150, v151
	v_add_f32_e32 v148, v148, v150
	v_add_f32_e32 v192, v192, v206
	v_add_f32_e32 v193, v193, v207
	v_add_f32_e32 v194, v194, v208
	v_add_f32_e32 v195, v195, v209
	v_add_f32_e32 v192, v192, v193
	v_add_f32_e32 v194, v194, v195
	v_add_f32_e32 v192, v192, v194
	v_add_f32_e32 v210, v210, v214
	v_add_f32_e32 v211, v211, v215
	v_add_f32_e32 v212, v212, v216
	v_add_f32_e32 v213, v213, v217
	v_add_f32_e32 v210, v210, v211
	v_add_f32_e32 v212, v212, v213
	v_add_f32_e32 v210, v210, v212
	v_add_f32_e32 v218, v218, v222
	v_add_f32_e32 v219, v219, v223
	v_add_f32_e32 v220, v220, v224
	v_add_f32_e32 v221, v221, v225
	v_add_f32_e32 v218, v218, v219
	v_add_f32_e32 v220, v220, v221
	v_add_f32_e32 v218, v218, v220
	v_add_f32_e32 v226, v226, v230
	v_add_f32_e32 v227, v227, v231
	v_add_f32_e32 v228, v228, v232
	v_add_f32_e32 v229, v229, v233
	v_add_f32_e32 v226, v226, v227
	v_add_f32_e32 v228, v228, v229
	v_add_f32_e32 v226, v226, v228
	v_add_f32_e32 v234, v234, v184
	v_add_f32_e32 v235, v235, v185
	v_add_f32_e32 v236, v236, v186
	v_add_f32_e32 v237, v237, v187
	v_add_f32_e32 v234, v234, v235
	v_add_f32_e32 v236, v236, v237
	v_add_f32_e32 v234, v234, v236
	ds_bpermute_b32 v133, v197, v132
	ds_bpermute_b32 v141, v197, v140
	ds_bpermute_b32 v149, v197, v148
	ds_bpermute_b32 v193, v197, v192
	ds_bpermute_b32 v211, v197, v210
	ds_bpermute_b32 v219, v197, v218
	ds_bpermute_b32 v227, v197, v226
	ds_bpermute_b32 v235, v197, v234
	s_waitcnt lgkmcnt(0)
	v_add_f32_e32 v132, v132, v133
	v_add_f32_e32 v140, v140, v141
	v_add_f32_e32 v148, v148, v149
	v_add_f32_e32 v192, v192, v193
	v_add_f32_e32 v210, v210, v211
	v_add_f32_e32 v218, v218, v219
	v_add_f32_e32 v226, v226, v227
	v_add_f32_e32 v234, v234, v235
	ds_bpermute_b32 v133, v239, v132
	ds_bpermute_b32 v141, v239, v140
	ds_bpermute_b32 v149, v239, v148
	ds_bpermute_b32 v193, v239, v192
	ds_bpermute_b32 v211, v239, v210
	ds_bpermute_b32 v219, v239, v218
	ds_bpermute_b32 v227, v239, v226
	ds_bpermute_b32 v235, v239, v234
	s_waitcnt lgkmcnt(0)
	v_add_f32_e32 v132, v132, v133
	v_add_f32_e32 v140, v140, v141
	v_add_f32_e32 v148, v148, v149
	v_add_f32_e32 v192, v192, v193
	v_add_f32_e32 v210, v210, v211
	v_add_f32_e32 v218, v218, v219
	v_add_f32_e32 v226, v226, v227
	v_add_f32_e32 v234, v234, v235
	v_fma_f32 v132, s66, v132, v199
	v_fma_f32 v140, s66, v140, v199
	v_fma_f32 v148, s66, v148, v199
	v_fma_f32 v192, s66, v192, v199
	v_fma_f32 v210, s66, v210, v199
	v_fma_f32 v218, s66, v218, v199
	v_fma_f32 v226, s66, v226, v199
	v_fma_f32 v234, s66, v234, v199
	v_rsq_f32_e32 v132, v132
	v_rsq_f32_e32 v140, v140
	v_rsq_f32_e32 v148, v148
	v_rsq_f32_e32 v192, v192
	v_rsq_f32_e32 v210, v210
	v_rsq_f32_e32 v218, v218
	v_rsq_f32_e32 v226, v226
	v_rsq_f32_e32 v234, v234
	ds_write_b32 v203, v132
	ds_write_b32 v203, v140 offset:64
	ds_write_b32 v203, v148 offset:128
	ds_write_b32 v203, v192 offset:192
	ds_write_b32 v203, v210 offset:512
	ds_write_b32 v203, v218 offset:576
	ds_write_b32 v203, v226 offset:640
	ds_write_b32 v203, v234 offset:704
	v_mul_f32_e32 v130, v182, v132
	v_mul_f32_e32 v131, v182, v140
	v_mul_f32_e32 v186, v182, v148
	v_mul_f32_e32 v187, v182, v192
	v_mul_f32_e32 v184, v182, v210
	v_mul_f32_e32 v185, v182, v218
	v_mul_f32_e32 v176, v182, v226
	v_mul_f32_e32 v177, v182, v234
	s_mov_b64 s[46:47], 0

; __device__ __forceinline__ float rowsum32(const float* ssp, int row, int nsl4, int fq) {
;     f32x4 v = {0.f, 0.f, 0.f, 0.f};
;     if (fq < nsl4) v = *(const f32x4*)(ssp + (size_t)row * 32 + 4 * fq);
;     if (fq + 4 < nsl4) v = v + *(const f32x4*)(ssp + (size_t)row * 32 + 4 * (fq + 4));
;     __device__ __forceinline__ void operator()(const f32x4 (&acc)[2][2][4][2], const Unit& u, int wr, int wc, int fr, int fq) const {
;         const int row0 = u.pm * BM + wr * 64 + fr;
;         const float sc = (u.pn < nscale) ? scale : 1.f;
;         float* sacc = nullptr; int slot0 = 0;
;         if (u.pn >= a_lo && u.pn < a_hi) { sacc = ssA; slot0 = (u.pn - a_lo) * 4 + wc; } else if (u.pn >= b_lo && u.pn < b_hi) { sacc = ssB; slot0 = (u.pn - b_lo) * 4 + wc; }
;         float rs[2][4];
;         if (!ss) {
; #pragma unroll
;             for (int ai = 0; ai < 2; ++ai)
; #pragma unroll
;                 for (int m = 0; m < 4; ++m) rs[ai][m] = sc;
;         } else if (u.pm != last_pm) {
; #pragma unroll
;             for (int ai = 0; ai < 2; ++ai)
; #pragma unroll
;                 for (int m = 0; m < 4; ++m) { const int row = row0 + ai * HALF + m * 16; const float r_ = __builtin_amdgcn_rsqf(rowsum32(ss, row, nsl4, fq) * inv_w + RMS_EPS);
;                     tab[ai * HALF + wr * 64 + m * 16 + fr] = r_; rs[ai][m] = r_ * sc; }
.LBB0_571:
	v_readlane_b32 s24, v248, 4
	s_cmp_lt_i32 s3, s24
	v_readlane_b32 s24, v248, 5
	s_cselect_b64 vcc, -1, 0
	v_lshl_add_u32 v172, s13, 8, v1
	v_mov_b32_e32 v130, s24
	v_cndmask_b32_e32 v182, 1.0, v130, vcc
	s_andn2_b64 vcc, exec, s[14:15]
	s_cbranch_vccnz .LBB0_609
	s_cmp_eq_u32 s13, s9
	s_mov_b64 s[44:45], -1
	s_cbranch_scc1 .LBB0_606
	v_mov_b32_e32 v174, v175
	v_mov_b64_e32 v[132:133], 0
	v_mov_b64_e32 v[134:135], 0
	v_mov_b64_e32 v[136:137], 0
	v_mov_b64_e32 v[138:139], 0
	v_mov_b64_e32 v[140:141], 0
	v_mov_b64_e32 v[142:143], 0
	v_mov_b64_e32 v[144:145], 0
	v_mov_b64_e32 v[146:147], 0
	v_mov_b64_e32 v[148:149], 0
	v_mov_b64_e32 v[150:151], 0
	v_mov_b64_e32 v[188:189], 0
	v_mov_b64_e32 v[190:191], 0
	v_mov_b64_e32 v[192:193], 0
	v_mov_b64_e32 v[194:195], 0
	v_mov_b64_e32 v[206:207], 0
	v_mov_b64_e32 v[208:209], 0
	v_mov_b64_e32 v[210:211], 0
	v_mov_b64_e32 v[212:213], 0
	v_mov_b64_e32 v[214:215], 0
	v_mov_b64_e32 v[216:217], 0
	v_mov_b64_e32 v[218:219], 0
	v_mov_b64_e32 v[220:221], 0
	v_mov_b64_e32 v[222:223], 0
	v_mov_b64_e32 v[224:225], 0
	v_mov_b64_e32 v[226:227], 0
	v_mov_b64_e32 v[228:229], 0
	v_mov_b64_e32 v[230:231], 0
	v_mov_b64_e32 v[232:233], 0
	v_mov_b64_e32 v[234:235], 0
	v_mov_b64_e32 v[236:237], 0
	v_mov_b64_e32 v[184:185], 0
	v_mov_b64_e32 v[186:187], 0
	v_lshlrev_b32_e32 v130, 7, v172
	v_mov_b32_e32 v131, 0
	v_add_u32_e32 v130, 0x1000, v130
	v_lshl_add_u64 v[152:153], v[164:165], 0, v[130:131]
	v_lshl_add_u64 v[196:197], v[166:167], 0, v[130:131]
	v_mov_b32_e32 v130, 0x4000
	v_lshl_add_u64 v[238:239], v[152:153], 0, v[130:131]
	v_lshl_add_u64 v[176:177], v[196:197], 0, v[130:131]
	s_and_saveexec_b64 s[44:45], s[38:39]
	s_cbranch_execz .Lrs_bfb_lo_done
	global_load_dwordx4 v[132:135], v[152:153], off offset:-4096
	global_load_dwordx4 v[140:143], v[152:153], off offset:-2048
	global_load_dwordx4 v[148:151], v[152:153], off
	global_load_dwordx4 v[192:195], v[152:153], off offset:2048
	global_load_dwordx4 v[210:213], v[238:239], off offset:-4096
	global_load_dwordx4 v[218:221], v[238:239], off offset:-2048
	global_load_dwordx4 v[226:229], v[238:239], off
	global_load_dwordx4 v[234:237], v[238:239], off offset:2048
.Lrs_bfb_lo_done:
	s_or_b64 exec, exec, s[44:45]
	s_and_saveexec_b64 s[44:45], s[40:41]
	s_cbranch_execz .Lrs_bfb_hi_done
	global_load_dwordx4 v[136:139], v[196:197], off offset:-4096
	global_load_dwordx4 v[144:147], v[196:197], off offset:-2048
	global_load_dwordx4 v[188:191], v[196:197], off
	global_load_dwordx4 v[206:209], v[196:197], off offset:2048
	global_load_dwordx4 v[214:217], v[176:177], off offset:-4096
	global_load_dwordx4 v[222:225], v[176:177], off offset:-2048
	global_load_dwordx4 v[230:233], v[176:177], off
	global_load_dwordx4 v[184:187], v[176:177], off offset:2048
; __device__ __forceinline__ float rowsum32(const float* ssp, int row, int nsl4, int fq) {
;     f32x4 v = {0.f, 0.f, 0.f, 0.f};
;     if (fq < nsl4) v = *(const f32x4*)(ssp + (size_t)row * 32 + 4 * fq);
;     if (fq + 4 < nsl4) v = v + *(const f32x4*)(ssp + (size_t)row * 32 + 4 * (fq + 4));
;     float s = (v[0] + v[1]) + (v[2] + v[3]);
;     s += __shfl_xor(s, 16); s += __shfl_xor(s, 32);
;     return s;
;     __device__ __forceinline__ void operator()(const f32x4 (&acc)[2][2][4][2], const Unit& u, int wr, int wc, int fr, int fq) const {
;     ...
;         } else if (u.pm != last_pm) {
; #pragma unroll
;             for (int ai = 0; ai < 2; ++ai)
; #pragma unroll
;                 for (int m = 0; m < 4; ++m) { const int row = row0 + ai * HALF + m * 16; const float r_ = __builtin_amdgcn_rsqf(rowsum32(ss, row, nsl4, fq) * inv_w + RMS_EPS);
;                     tab[ai * HALF + wr * 64 + m * 16 + fr] = r_; rs[ai][m] = r_ * sc; }
;             last_pm = u.pm;
.Lrs_bfb_hi_done:
	s_or_b64 exec, exec, s[44:45]
	v_and_b32_e32 v153, 64, v200
	v_xor_b32_e32 v130, 16, v200
	v_add_u32_e32 v153, 64, v153
	v_xor_b32_e32 v131, 32, v200
	v_cmp_lt_i32_e32 vcc, v130, v153
	s_nop 1
	v_cndmask_b32_e32 v130, v200, v130, vcc
	v_cmp_lt_i32_e32 vcc, v131, v153
	v_lshlrev_b32_e32 v197, 2, v130
	s_nop 1
	v_cndmask_b32_e32 v131, v200, v131, vcc
	v_lshlrev_b32_e32 v239, 2, v131
	s_waitcnt vmcnt(0)
	v_add_f32_e32 v132, v132, v136
	v_add_f32_e32 v133, v133, v137
	v_add_f32_e32 v134, v134, v138
	v_add_f32_e32 v135, v135, v139
	v_add_f32_e32 v132, v132, v133
	v_add_f32_e32 v134, v134, v135
	v_add_f32_e32 v132, v132, v134
	v_add_f32_e32 v140, v140, v144
	v_add_f32_e32 v141, v141, v145
	v_add_f32_e32 v142, v142, v146
	v_add_f32_e32 v143, v143, v147
	v_add_f32_e32 v140, v140, v141
	v_add_f32_e32 v142, v142, v143
	v_add_f32_e32 v140, v140, v142
	v_add_f32_e32 v148, v148, v188
	v_add_f32_e32 v149, v149, v189
	v_add_f32_e32 v150, v150, v190
	v_add_f32_e32 v151, v151, v191
	v_add_f32_e32 v148, v148, v149
	v_add_f32_e32 v150, v150, v151
	v_add_f32_e32 v148, v148, v150
	v_add_f32_e32 v192, v192, v206
	v_add_f32_e32 v193, v193, v207
	v_add_f32_e32 v194, v194, v208
	v_add_f32_e32 v195, v195, v209
	v_add_f32_e32 v192, v192, v193
	v_add_f32_e32 v194, v194, v195
	v_add_f32_e32 v192, v192, v194
	v_add_f32_e32 v210, v210, v214
	v_add_f32_e32 v211, v211, v215
	v_add_f32_e32 v212, v212, v216
	v_add_f32_e32 v213, v213, v217
	v_add_f32_e32 v210, v210, v211
	v_add_f32_e32 v212, v212, v213
	v_add_f32_e32 v210, v210, v212
	v_add_f32_e32 v218, v218, v222
	v_add_f32_e32 v219, v219, v223
	v_add_f32_e32 v220, v220, v224
	v_add_f32_e32 v221, v221, v225
	v_add_f32_e32 v218, v218, v219
	v_add_f32_e32 v220, v220, v221
	v_add_f32_e32 v218, v218, v220
	v_add_f32_e32 v226, v226, v230
	v_add_f32_e32 v227, v227, v231
	v_add_f32_e32 v228, v228, v232
	v_add_f32_e32 v229, v229, v233
	v_add_f32_e32 v226, v226, v227
	v_add_f32_e32 v228, v228, v229
	v_add_f32_e32 v226, v226, v228
	v_add_f32_e32 v234, v234, v184
	v_add_f32_e32 v235, v235, v185
	v_add_f32_e32 v236, v236, v186
	v_add_f32_e32 v237, v237, v187
	v_add_f32_e32 v234, v234, v235
	v_add_f32_e32 v236, v236, v237
	v_add_f32_e32 v234, v234, v236
	ds_bpermute_b32 v133, v197, v132
	ds_bpermute_b32 v141, v197, v140
	ds_bpermute_b32 v149, v197, v148
	ds_bpermute_b32 v193, v197, v192
	ds_bpermute_b32 v211, v197, v210
	ds_bpermute_b32 v219, v197, v218
	ds_bpermute_b32 v227, v197, v226
	ds_bpermute_b32 v235, v197, v234
	s_waitcnt lgkmcnt(0)
	v_add_f32_e32 v132, v132, v133
	v_add_f32_e32 v140, v140, v141
	v_add_f32_e32 v148, v148, v149
	v_add_f32_e32 v192, v192, v193
	v_add_f32_e32 v210, v210, v211
	v_add_f32_e32 v218, v218, v219
	v_add_f32_e32 v226, v226, v227
	v_add_f32_e32 v234, v234, v235
	ds_bpermute_b32 v133, v239, v132
	ds_bpermute_b32 v141, v239, v140
	ds_bpermute_b32 v149, v239, v148
	ds_bpermute_b32 v193, v239, v192
	ds_bpermute_b32 v211, v239, v210
	ds_bpermute_b32 v219, v239, v218
	ds_bpermute_b32 v227, v239, v226
	ds_bpermute_b32 v235, v239, v234
	s_waitcnt lgkmcnt(0)
	v_add_f32_e32 v132, v132, v133
	v_add_f32_e32 v140, v140, v141
	v_add_f32_e32 v148, v148, v149
	v_add_f32_e32 v192, v192, v193
	v_add_f32_e32 v210, v210, v211
	v_add_f32_e32 v218, v218, v219
	v_add_f32_e32 v226, v226, v227
	v_add_f32_e32 v234, v234, v235
	v_fma_f32 v132, s66, v132, v199
	v_fma_f32 v140, s66, v140, v199
	v_fma_f32 v148, s66, v148, v199
	v_fma_f32 v192, s66, v192, v199
	v_fma_f32 v210, s66, v210, v199
	v_fma_f32 v218, s66, v218, v199
	v_fma_f32 v226, s66, v226, v199
	v_fma_f32 v234, s66, v234, v199
	v_rsq_f32_e32 v132, v132
	v_rsq_f32_e32 v140, v140
	v_rsq_f32_e32 v148, v148
	v_rsq_f32_e32 v192, v192
	v_rsq_f32_e32 v210, v210
	v_rsq_f32_e32 v218, v218
	v_rsq_f32_e32 v226, v226
	v_rsq_f32_e32 v234, v234
	ds_write_b32 v203, v132
	ds_write_b32 v203, v140 offset:64
	ds_write_b32 v203, v148 offset:128
	ds_write_b32 v203, v192 offset:192
	ds_write_b32 v203, v210 offset:512
	ds_write_b32 v203, v218 offset:576
	ds_write_b32 v203, v226 offset:640
	ds_write_b32 v203, v234 offset:704
	v_mul_f32_e32 v130, v182, v132
	v_mul_f32_e32 v131, v182, v140
	v_mul_f32_e32 v186, v182, v148
	v_mul_f32_e32 v187, v182, v192
	v_mul_f32_e32 v184, v182, v210
	v_mul_f32_e32 v185, v182, v218
	v_mul_f32_e32 v176, v182, v226
	v_mul_f32_e32 v177, v182, v234
	s_mov_b64 s[44:45], 0
